# v94: mLSTM state pass, latent chunk loop: state-snapshot stores issued behind the last K^T wait of the chunk (in front they made every load wait for the stores' acknowledgements, the counter being in
# speedup vs baseline: 1.0011x; 1.0011x over previous
.LBB0_285:
	v_sub_f32_e32 v51, s61, v54
	s_waitcnt vmcnt(12)
	v_add_f32_e32 v50, v50, v51
	v_sub_f32_e32 v51, s61, v55
	v_add_f32_e32 v0, v0, v51
	v_max_f32_e32 v51, v50, v0
	ds_bpermute_b32 v52, v141, v51
	v_add_f32_e32 v53, s61, v151
	s_ashr_i32 s61, s60, 31
	s_lshl_b64 s[52:53], s[60:61], 1
	s_add_u32 s60, s93, s52
	s_waitcnt lgkmcnt(0)
	v_max_f32_e32 v52, v52, v52
	v_max_f32_e32 v51, v51, v52
	ds_bpermute_b32 v52, v142, v51
	s_addc_u32 s61, s94, s53
	s_waitcnt lgkmcnt(0)
	v_max_f32_e32 v52, v52, v52
	v_max_f32_e32 v51, v51, v52
	ds_bpermute_b32 v52, v143, v51
	s_waitcnt lgkmcnt(0)
	v_max_f32_e32 v52, v52, v52
	v_max_f32_e32 v51, v51, v52
	ds_bpermute_b32 v52, v144, v51
	s_waitcnt lgkmcnt(0)
	v_max_f32_e32 v52, v52, v52
	v_max_f32_e32 v51, v51, v52
	ds_bpermute_b32 v52, v145, v51
	s_waitcnt lgkmcnt(0)
	v_max_f32_e32 v52, v52, v52
	v_max_f32_e32 v51, v51, v52
	ds_bpermute_b32 v52, v146, v51
	s_waitcnt lgkmcnt(0)
	v_max3_f32 v153, v53, v51, v52
	v_sub_f32_e32 v50, v50, v153
	v_sub_f32_e32 v0, v0, v153
	v_mul_f32_e32 v50, 0x3fb8aa3b, v50
	v_mul_f32_e32 v0, 0x3fb8aa3b, v0
	v_exp_f32_e32 v50, v50
	v_exp_f32_e32 v51, v0
	v_sub_f32_e32 v0, v53, v153
	v_mul_f32_e32 v0, 0x3fb8aa3b, v0
	v_exp_f32_e32 v0, v0
	ds_write_b64 v147, v[50:51]
	ds_read_b128 v[82:85], v148
	ds_read_b128 v[86:89], v148 offset:16
	s_waitcnt vmcnt(11)
	v_mov_b32_e32 v90, v180
	v_mov_b32_e32 v91, v181
	v_mov_b32_e32 v92, v182
	v_mov_b32_e32 v93, v183
	v_pk_mul_f32 v[80:81], v[48:49], v[0:1] op_sel_hi:[1,0]
	v_pk_mul_f32 v[78:79], v[46:47], v[0:1] op_sel_hi:[1,0]
	v_pk_mul_f32 v[76:77], v[44:45], v[0:1] op_sel_hi:[1,0]
	v_pk_mul_f32 v[74:75], v[42:43], v[0:1] op_sel_hi:[1,0]
	v_pk_mul_f32 v[72:73], v[32:33], v[0:1] op_sel_hi:[1,0]
	v_pk_mul_f32 v[70:71], v[30:31], v[0:1] op_sel_hi:[1,0]
	v_pk_mul_f32 v[68:69], v[28:29], v[0:1] op_sel_hi:[1,0]
	v_pk_mul_f32 v[66:67], v[26:27], v[0:1] op_sel_hi:[1,0]
	v_pk_mul_f32 v[64:65], v[16:17], v[0:1] op_sel_hi:[1,0]
	v_pk_mul_f32 v[62:63], v[14:15], v[0:1] op_sel_hi:[1,0]
	v_pk_mul_f32 v[60:61], v[12:13], v[0:1] op_sel_hi:[1,0]
	v_pk_mul_f32 v[58:59], v[10:11], v[0:1] op_sel_hi:[1,0]
	v_pk_mul_f32 v[56:57], v[8:9], v[0:1] op_sel_hi:[1,0]
	v_pk_mul_f32 v[54:55], v[6:7], v[0:1] op_sel_hi:[1,0]
	v_pk_mul_f32 v[52:53], v[4:5], v[0:1] op_sel_hi:[1,0]
	v_pk_mul_f32 v[50:51], v[2:3], v[0:1] op_sel_hi:[1,0]
	s_waitcnt vmcnt(8)
	v_lshlrev_b32_e32 v94, 16, v90
	v_and_b32_e32 v95, 0xffff0000, v90
	v_lshlrev_b32_e32 v90, 16, v91
	v_and_b32_e32 v91, 0xffff0000, v91
	s_waitcnt lgkmcnt(1)
	v_pk_mul_f32 v[84:85], v[84:85], v[90:91]
	v_lshlrev_b32_e32 v90, 16, v92
	v_and_b32_e32 v91, 0xffff0000, v92
	v_pk_mul_f32 v[82:83], v[82:83], v[94:95]
	s_waitcnt lgkmcnt(0)
	v_pk_mul_f32 v[86:87], v[86:87], v[90:91]
	v_lshlrev_b32_e32 v90, 16, v93
	v_and_b32_e32 v91, 0xffff0000, v93
	v_pk_mul_f32 v[88:89], v[88:89], v[90:91]
	v_mov_b32_e32 v90, v82
	v_mov_b32_e32 v91, v86
	v_mov_b32_e32 v92, v83
	v_mov_b32_e32 v93, v87
	v_pk_add_f32 v[90:91], v[90:91], v[92:93]
	v_mov_b32_e32 v92, v84
	v_mov_b32_e32 v93, v88
	v_mov_b32_e32 v94, v85
	v_mov_b32_e32 v95, v89
	v_pk_add_f32 v[92:93], v[92:93], v[94:95]
	v_cvt_pk_bf16_f32 v82, v82, v83
	v_pk_add_f32 v[90:91], v[90:91], v[92:93]
	v_cvt_pk_bf16_f32 v83, v84, v85
	v_pk_add_f32 v[108:109], v[90:91], v[90:91] op_sel:[0,1] op_sel_hi:[1,0]
	v_cvt_pk_bf16_f32 v84, v86, v87
	v_cvt_pk_bf16_f32 v85, v88, v89
	ds_read_b128 v[86:89], v148 offset:128
	ds_read_b128 v[90:93], v148 offset:144
	s_waitcnt vmcnt(10)
	v_mov_b32_e32 v94, v184
	v_mov_b32_e32 v95, v185
	v_mov_b32_e32 v96, v186
	v_mov_b32_e32 v97, v187
	s_waitcnt vmcnt(8)
	v_lshlrev_b32_e32 v98, 16, v94
	v_and_b32_e32 v99, 0xffff0000, v94
	v_lshlrev_b32_e32 v94, 16, v95
	v_and_b32_e32 v95, 0xffff0000, v95
	s_waitcnt lgkmcnt(1)
	v_pk_mul_f32 v[88:89], v[88:89], v[94:95]
	v_lshlrev_b32_e32 v94, 16, v96
	v_and_b32_e32 v95, 0xffff0000, v96
	v_pk_mul_f32 v[86:87], v[86:87], v[98:99]
	s_waitcnt lgkmcnt(0)
	v_pk_mul_f32 v[90:91], v[90:91], v[94:95]
	v_lshlrev_b32_e32 v94, 16, v97
	v_and_b32_e32 v95, 0xffff0000, v97
	v_pk_mul_f32 v[92:93], v[92:93], v[94:95]
	v_mov_b32_e32 v94, v86
	v_mov_b32_e32 v95, v88
	v_mov_b32_e32 v96, v87
	v_mov_b32_e32 v97, v89
	v_pk_add_f32 v[94:95], v[94:95], v[96:97]
	v_mov_b32_e32 v96, v91
	v_pk_add_f32 v[110:111], v[94:95], v[94:95] op_sel:[0,1] op_sel_hi:[1,0]
	v_mov_b32_e32 v94, v90
	v_mov_b32_e32 v95, v92
	v_mov_b32_e32 v97, v93
	v_pk_add_f32 v[94:95], v[94:95], v[96:97]
	v_cvt_pk_bf16_f32 v86, v86, v87
	v_pk_add_f32 v[112:113], v[94:95], v[94:95] op_sel:[0,1] op_sel_hi:[1,0]
	v_cvt_pk_bf16_f32 v87, v88, v89
	v_cvt_pk_bf16_f32 v88, v90, v91
	v_cvt_pk_bf16_f32 v89, v92, v93
	ds_read_b128 v[94:97], v148 offset:256
	ds_read_b128 v[90:93], v148 offset:272
	s_waitcnt vmcnt(9)
	v_mov_b32_e32 v98, v188
	v_mov_b32_e32 v99, v189
	v_mov_b32_e32 v100, v190
	v_mov_b32_e32 v101, v191
	s_waitcnt vmcnt(8)
	v_lshlrev_b32_e32 v104, 16, v98
	v_and_b32_e32 v105, 0xffff0000, v98
	v_lshlrev_b32_e32 v98, 16, v99
	v_and_b32_e32 v99, 0xffff0000, v99
	v_lshlrev_b32_e32 v114, 16, v100
	v_and_b32_e32 v115, 0xffff0000, v100
	v_lshlrev_b32_e32 v100, 16, v101
	v_and_b32_e32 v101, 0xffff0000, v101
	s_waitcnt lgkmcnt(1)
	v_pk_mul_f32 v[122:123], v[94:95], v[104:105]
	v_pk_mul_f32 v[154:155], v[96:97], v[98:99]
	s_waitcnt lgkmcnt(0)
	v_pk_mul_f32 v[158:159], v[92:93], v[100:101]
	v_pk_fma_f32 v[118:119], v[94:95], v[104:105], v[122:123] op_sel:[0,0,1] op_sel_hi:[1,1,0]
	v_pk_fma_f32 v[120:121], v[96:97], v[98:99], v[154:155] op_sel:[0,0,1] op_sel_hi:[1,1,0]
	v_pk_fma_f32 v[116:117], v[92:93], v[100:101], v[158:159] op_sel:[0,0,1] op_sel_hi:[1,1,0]
	ds_read_b128 v[98:101], v148 offset:384
	ds_read_b128 v[94:97], v148 offset:400
	s_waitcnt vmcnt(8)
	v_mov_b32_e32 v102, v192
	v_mov_b32_e32 v103, v193
	v_mov_b32_e32 v104, v194
	v_mov_b32_e32 v105, v195
	v_pk_mul_f32 v[156:157], v[90:91], v[114:115]
	v_cvt_pk_bf16_f32 v93, v158, v159
	v_pk_fma_f32 v[114:115], v[90:91], v[114:115], v[156:157] op_sel:[0,0,1] op_sel_hi:[1,1,0]
	v_cvt_pk_bf16_f32 v90, v122, v123
	v_cvt_pk_bf16_f32 v91, v154, v155
	v_cvt_pk_bf16_f32 v92, v156, v157
	s_waitcnt vmcnt(8)
	s_cmp_lg_u32 s97, 0
	s_cselect_b64 s[52:53], -1, 0
	s_cmp_lt_u32 s97, s80
	s_cselect_b64 s[60:61], -1, 0
	s_and_b64 s[52:53], s[52:53], s[60:61]
	s_or_b64 s[52:53], s[40:41], s[52:53]
	s_andn2_b64 vcc, exec, s[52:53]
	s_cbranch_vccnz .Lml1s_skip
	v_mov_b32_e32 v207, 0
	s_add_i32 s60, s95, s97
	s_and_b64 s[52:53], s[40:41], exec
	s_cselect_b32 s52, s60, s85
	s_ashr_i32 s53, s52, 31
	s_lshl_b64 s[60:61], s[52:53], 17
	s_mul_hi_i32 s101, s52, 0x440
	s_mul_i32 s100, s52, 0x440
	s_add_u32 s52, s3, s60
	v_mov_b32_e32 v206, v127
	s_addc_u32 s53, s92, s61
	v_cvt_pk_bf16_f32 v203, v46, s0
	global_store_short v206, v203, s[52:53]
	v_cvt_pk_bf16_f32 v203, v47, s0
	global_store_short v206, v203, s[52:53] offset:512
	v_cvt_pk_bf16_f32 v203, v48, s0
	global_store_short v206, v203, s[52:53] offset:1024
	v_cvt_pk_bf16_f32 v203, v49, s0
	v_lshl_add_u64 v[204:205], s[52:53], 0, v[206:207]
	global_store_short v206, v203, s[52:53] offset:1536
	s_mov_b64 s[52:53], 0x2000
	v_lshl_add_u64 v[204:205], v[204:205], 0, s[52:53]
	v_cvt_pk_bf16_f32 v206, v42, s0
	global_store_short v[204:205], v206, off
	v_cvt_pk_bf16_f32 v206, v43, s0
	global_store_short v[204:205], v206, off offset:512
	v_cvt_pk_bf16_f32 v206, v44, s0
	global_store_short v[204:205], v206, off offset:1024
	v_cvt_pk_bf16_f32 v206, v45, s0
	global_store_short v[204:205], v206, off offset:1536
	v_lshl_add_u64 v[204:205], v[204:205], 0, s[52:53]
	v_cvt_pk_bf16_f32 v206, v30, s0
	global_store_short v[204:205], v206, off
	v_cvt_pk_bf16_f32 v206, v31, s0
	global_store_short v[204:205], v206, off offset:512
	v_cvt_pk_bf16_f32 v206, v32, s0
	global_store_short v[204:205], v206, off offset:1024
	v_cvt_pk_bf16_f32 v206, v33, s0
	global_store_short v[204:205], v206, off offset:1536
	v_lshl_add_u64 v[204:205], v[204:205], 0, s[52:53]
	v_cvt_pk_bf16_f32 v206, v26, s0
	global_store_short v[204:205], v206, off
	v_cvt_pk_bf16_f32 v206, v27, s0
	global_store_short v[204:205], v206, off offset:512
	v_cvt_pk_bf16_f32 v206, v28, s0
	global_store_short v[204:205], v206, off offset:1024
	v_cvt_pk_bf16_f32 v206, v29, s0
	global_store_short v[204:205], v206, off offset:1536
	v_lshl_add_u64 v[204:205], v[204:205], 0, s[52:53]
	v_cvt_pk_bf16_f32 v206, v14, s0
	global_store_short v[204:205], v206, off
	v_cvt_pk_bf16_f32 v206, v15, s0
	global_store_short v[204:205], v206, off offset:512
	v_cvt_pk_bf16_f32 v206, v16, s0
	global_store_short v[204:205], v206, off offset:1024
	v_cvt_pk_bf16_f32 v206, v17, s0
	global_store_short v[204:205], v206, off offset:1536
	v_lshl_add_u64 v[204:205], v[204:205], 0, s[52:53]
	v_cvt_pk_bf16_f32 v206, v10, s0
	global_store_short v[204:205], v206, off
	v_cvt_pk_bf16_f32 v206, v11, s0
	global_store_short v[204:205], v206, off offset:512
	v_cvt_pk_bf16_f32 v206, v12, s0
	global_store_short v[204:205], v206, off offset:1024
	v_cvt_pk_bf16_f32 v206, v13, s0
	global_store_short v[204:205], v206, off offset:1536
	v_lshl_add_u64 v[204:205], v[204:205], 0, s[52:53]
	v_cvt_pk_bf16_f32 v206, v6, s0
	global_store_short v[204:205], v206, off
	v_cvt_pk_bf16_f32 v206, v7, s0
	global_store_short v[204:205], v206, off offset:512
	v_cvt_pk_bf16_f32 v206, v8, s0
	global_store_short v[204:205], v206, off offset:1024
	v_cvt_pk_bf16_f32 v206, v9, s0
	global_store_short v[204:205], v206, off offset:1536
	v_lshl_add_u64 v[204:205], v[204:205], 0, s[52:53]
	v_cvt_pk_bf16_f32 v206, v2, s0
	global_store_short v[204:205], v206, off
	v_cvt_pk_bf16_f32 v206, v3, s0
	global_store_short v[204:205], v206, off offset:512
	v_cvt_pk_bf16_f32 v206, v4, s0
	global_store_short v[204:205], v206, off offset:1024
	v_cvt_pk_bf16_f32 v206, v5, s0
	s_add_u32 s60, s66, s100
	global_store_short v[204:205], v206, off offset:1536
	v_lshl_add_u64 v[204:205], v[204:205], 0, s[52:53]
	s_addc_u32 s61, s67, s101
	s_and_saveexec_b64 s[52:53], s[56:57]
	s_cbranch_execz .Lml1s_a
	v_lshl_add_u64 v[204:205], v[106:107], 2, s[60:61]
	global_store_dword v[204:205], v152, off

.Lml1s_skip:
	v_lshlrev_b32_e32 v122, 16, v102
	v_and_b32_e32 v123, 0xffff0000, v102
	v_lshlrev_b32_e32 v102, 16, v103
	v_and_b32_e32 v103, 0xffff0000, v103
	s_waitcnt lgkmcnt(1)
	v_pk_mul_f32 v[98:99], v[98:99], v[122:123]
	v_pk_mul_f32 v[122:123], v[100:101], v[102:103]
	v_lshlrev_b32_e32 v100, 16, v104
	v_and_b32_e32 v101, 0xffff0000, v104
	s_waitcnt lgkmcnt(0)
	v_pk_mul_f32 v[102:103], v[94:95], v[100:101]
	v_lshlrev_b32_e32 v94, 16, v105
	v_and_b32_e32 v95, 0xffff0000, v105
	v_pk_mul_f32 v[100:101], v[96:97], v[94:95]
	v_cvt_pk_bf16_f32 v94, v98, v99
	v_cvt_pk_bf16_f32 v95, v122, v123
	v_cvt_pk_bf16_f32 v96, v102, v103
	v_cvt_pk_bf16_f32 v97, v100, v101
	ds_read_b128 v[154:157], v149
	s_waitcnt lgkmcnt(0)
	v_mfma_f32_16x16x32_bf16 v[78:81], v[154:157], v[82:85], v[78:81]
	ds_read_b128 v[154:157], v149 offset:4352
	s_waitcnt lgkmcnt(0)
	v_mfma_f32_16x16x32_bf16 v[154:157], v[154:157], v[82:85], v[74:77]
	s_nop 2
	ds_read_b128 v[74:77], v149 offset:64
	s_waitcnt lgkmcnt(0)
	v_mfma_f32_16x16x32_bf16 v[74:77], v[74:77], v[86:89], v[78:81]
	s_nop 2
	ds_read_b128 v[78:81], v149 offset:128
	s_waitcnt lgkmcnt(0)
	v_mfma_f32_16x16x32_bf16 v[74:77], v[78:81], v[90:93], v[74:77]
	ds_read_b128 v[78:81], v149 offset:192
	s_waitcnt lgkmcnt(0)
	v_mfma_f32_16x16x32_bf16 v[74:77], v[78:81], v[94:97], v[74:77]
	ds_read_b128 v[78:81], v149 offset:4416
	s_waitcnt lgkmcnt(0)
	v_mfma_f32_16x16x32_bf16 v[78:81], v[78:81], v[86:89], v[154:157]
	s_nop 2
	ds_read_b128 v[154:157], v149 offset:4480
	s_waitcnt lgkmcnt(0)
	v_mfma_f32_16x16x32_bf16 v[78:81], v[154:157], v[90:93], v[78:81]
	ds_read_b128 v[154:157], v149 offset:4544
	s_waitcnt lgkmcnt(0)
	v_mfma_f32_16x16x32_bf16 v[78:81], v[154:157], v[94:97], v[78:81]
	ds_read_b128 v[154:157], v149 offset:8704
	s_waitcnt lgkmcnt(0)
	v_mfma_f32_16x16x32_bf16 v[70:73], v[154:157], v[82:85], v[70:73]
	ds_read_b128 v[154:157], v149 offset:8768
	s_waitcnt lgkmcnt(0)
	v_mfma_f32_16x16x32_bf16 v[70:73], v[154:157], v[86:89], v[70:73]
	ds_read_b128 v[154:157], v149 offset:8832
	s_waitcnt lgkmcnt(0)
	v_mfma_f32_16x16x32_bf16 v[70:73], v[154:157], v[90:93], v[70:73]
	ds_read_b128 v[154:157], v149 offset:8896
	s_waitcnt lgkmcnt(0)
	v_mfma_f32_16x16x32_bf16 v[70:73], v[154:157], v[94:97], v[70:73]
	ds_read_b128 v[154:157], v149 offset:13056
	s_waitcnt lgkmcnt(0)
	v_mfma_f32_16x16x32_bf16 v[66:69], v[154:157], v[82:85], v[66:69]
	ds_read_b128 v[154:157], v149 offset:13120
	s_waitcnt lgkmcnt(0)
	v_mfma_f32_16x16x32_bf16 v[66:69], v[154:157], v[86:89], v[66:69]
	ds_read_b128 v[154:157], v149 offset:13184
	s_waitcnt lgkmcnt(0)
	v_mfma_f32_16x16x32_bf16 v[66:69], v[154:157], v[90:93], v[66:69]
	ds_read_b128 v[154:157], v149 offset:13248
	s_waitcnt lgkmcnt(0)
	v_mfma_f32_16x16x32_bf16 v[66:69], v[154:157], v[94:97], v[66:69]
	ds_read_b128 v[154:157], v149 offset:17408
	v_mov_b32_e32 v119, v102
	v_mov_b32_e32 v121, v103
	v_mov_b32_e32 v115, v100
	v_mov_b32_e32 v117, v101
	v_mov_b32_e32 v111, v122
	v_mov_b32_e32 v113, v123
	v_mov_b32_e32 v109, v98
	v_mov_b32_e32 v98, v1
	s_waitcnt lgkmcnt(0)
	v_mfma_f32_16x16x32_bf16 v[62:65], v[154:157], v[82:85], v[62:65]
	ds_read_b128 v[154:157], v149 offset:17472
	s_waitcnt lgkmcnt(0)
	v_mfma_f32_16x16x32_bf16 v[62:65], v[154:157], v[86:89], v[62:65]
	ds_read_b128 v[154:157], v149 offset:17536
	s_waitcnt lgkmcnt(0)
	v_mfma_f32_16x16x32_bf16 v[62:65], v[154:157], v[90:93], v[62:65]
	ds_read_b128 v[154:157], v149 offset:17600
	s_waitcnt lgkmcnt(0)
	v_mfma_f32_16x16x32_bf16 v[62:65], v[154:157], v[94:97], v[62:65]
	ds_read_b128 v[154:157], v149 offset:21952
	ds_read_b128 v[158:161], v149 offset:21888
	ds_read_b128 v[162:165], v149 offset:21824
	ds_read_b128 v[170:173], v149 offset:21760
	s_waitcnt lgkmcnt(0)
	v_mfma_f32_16x16x32_bf16 v[58:61], v[170:173], v[82:85], v[58:61]
	v_mfma_f32_16x16x32_bf16 v[58:61], v[162:165], v[86:89], v[58:61]
	v_mfma_f32_16x16x32_bf16 v[58:61], v[158:161], v[90:93], v[58:61]
	v_mfma_f32_16x16x32_bf16 v[58:61], v[154:157], v[94:97], v[58:61]
	ds_read_b128 v[154:157], v149 offset:26304
	ds_read_b128 v[158:161], v149 offset:26240
	ds_read_b128 v[162:165], v149 offset:26176
	ds_read_b128 v[170:173], v149 offset:26112
	s_waitcnt lgkmcnt(0)
	v_mfma_f32_16x16x32_bf16 v[54:57], v[170:173], v[82:85], v[54:57]
	v_mfma_f32_16x16x32_bf16 v[54:57], v[162:165], v[86:89], v[54:57]
	v_mfma_f32_16x16x32_bf16 v[54:57], v[158:161], v[90:93], v[54:57]
	v_mfma_f32_16x16x32_bf16 v[54:57], v[154:157], v[94:97], v[54:57]
	ds_read_b128 v[154:157], v149 offset:30656
	ds_read_b128 v[158:161], v149 offset:30592
	ds_read_b128 v[162:165], v149 offset:30528
	ds_read_b128 v[170:173], v149 offset:30464
	s_waitcnt lgkmcnt(0)
	v_mfma_f32_16x16x32_bf16 v[50:53], v[170:173], v[82:85], v[50:53]
	v_add_f32_e64 v84, v118, v120
	v_add_f32_e64 v85, v119, v121
	v_pk_add_f32 v[82:83], v[110:111], v[112:113]
	v_mfma_f32_16x16x32_bf16 v[50:53], v[162:165], v[86:89], v[50:53]
	v_add_f32_e64 v86, v114, v116
	v_add_f32_e64 v87, v115, v117
	v_pk_add_f32 v[84:85], v[84:85], v[86:87]
	v_mfma_f32_16x16x32_bf16 v[50:53], v[158:161], v[90:93], v[50:53]
	v_add_f32_e64 v86, v108, v98
	v_add_f32_e64 v87, v109, v99
	v_pk_add_f32 v[82:83], v[86:87], v[82:83]
	v_mfma_f32_16x16x32_bf16 v[50:53], v[154:157], v[94:97], v[50:53]
	v_add_f32_e64 v82, v82, v84
	v_add_f32_e64 v83, v83, v85
	v_add_f32_e32 v82, v82, v83
	ds_bpermute_b32 v83, v145, v82
	s_add_i32 s81, s81, -1
	s_mov_b64 s[60:61], 0
	s_waitcnt lgkmcnt(0)
	v_add_f32_e32 v82, v82, v83
	ds_bpermute_b32 v83, v146, v82
	s_waitcnt lgkmcnt(0)
	v_add_f32_e32 v82, v82, v83
	v_fmac_f32_e32 v82, v152, v0

.LBB0_287:
	s_cmp_lg_u32 s97, 0
	s_cselect_b64 s[52:53], -1, 0
	s_cmp_lt_u32 s97, s80
	s_cselect_b64 s[60:61], -1, 0
	s_and_b64 s[52:53], s[52:53], s[60:61]
	s_or_b64 s[52:53], s[40:41], s[52:53]
	s_waitcnt vmcnt(8)
	v_mov_b32_e32 v5, v53
	v_mov_b32_e32 v4, v52
	v_mov_b32_e32 v3, v51
	v_mov_b32_e32 v2, v50
	v_mov_b32_e32 v9, v57
	v_mov_b32_e32 v8, v56
	v_mov_b32_e32 v7, v55
	v_mov_b32_e32 v6, v54
	v_mov_b32_e32 v13, v61
	v_mov_b32_e32 v12, v60
	v_mov_b32_e32 v11, v59
	v_mov_b32_e32 v10, v58
	v_mov_b32_e32 v17, v65
	v_mov_b32_e32 v16, v64
	v_mov_b32_e32 v15, v63
	v_mov_b32_e32 v14, v62
	v_mov_b32_e32 v29, v69
	v_mov_b32_e32 v28, v68
	v_mov_b32_e32 v27, v67
	v_mov_b32_e32 v26, v66
	v_mov_b32_e32 v33, v73
	v_mov_b32_e32 v32, v72
	v_mov_b32_e32 v31, v71
	v_mov_b32_e32 v30, v70
	v_mov_b32_e32 v45, v81
	v_mov_b32_e32 v44, v80
	v_mov_b32_e32 v43, v79
	v_mov_b32_e32 v42, v78
	v_mov_b32_e32 v49, v77
	v_mov_b32_e32 v48, v76
	v_mov_b32_e32 v47, v75
	v_mov_b32_e32 v46, v74
	v_mov_b32_e32 v151, v153
	s_andn2_b64 vcc, exec, s[52:53]
	v_mov_b32_e32 v152, v82
	s_cbranch_vccnz .LBB0_293
	s_cmp_lg_u32 s62, s97
	s_cbranch_scc1 .LBB0_293
	s_add_i32 s60, s95, s97
	s_and_b64 s[52:53], s[40:41], exec
	s_cselect_b32 s52, s60, s85
	s_ashr_i32 s53, s52, 31
	s_lshl_b64 s[60:61], s[52:53], 17
	s_mul_hi_i32 s96, s52, 0x440
	s_mul_i32 vcc_lo, s52, 0x440
	s_add_u32 s52, s3, s60
	v_mov_b32_e32 v0, v127
	s_addc_u32 s53, s92, s61
	v_cvt_pk_bf16_f32 v52, v46, s0
	global_store_short v0, v52, s[52:53]
	v_cvt_pk_bf16_f32 v52, v47, s0
	global_store_short v0, v52, s[52:53] offset:512
	v_cvt_pk_bf16_f32 v52, v48, s0
	global_store_short v0, v52, s[52:53] offset:1024
	v_cvt_pk_bf16_f32 v52, v49, s0
	v_lshl_add_u64 v[50:51], s[52:53], 0, v[0:1]
	global_store_short v0, v52, s[52:53] offset:1536
	s_mov_b64 s[52:53], 0x2000
	v_lshl_add_u64 v[50:51], v[50:51], 0, s[52:53]
	v_cvt_pk_bf16_f32 v0, v42, s0
	global_store_short v[50:51], v0, off
	v_cvt_pk_bf16_f32 v0, v43, s0
	global_store_short v[50:51], v0, off offset:512
	v_cvt_pk_bf16_f32 v0, v44, s0
	global_store_short v[50:51], v0, off offset:1024
	v_cvt_pk_bf16_f32 v0, v45, s0
	global_store_short v[50:51], v0, off offset:1536
	v_lshl_add_u64 v[50:51], v[50:51], 0, s[52:53]
	v_cvt_pk_bf16_f32 v0, v30, s0
	global_store_short v[50:51], v0, off
	v_cvt_pk_bf16_f32 v0, v31, s0
	global_store_short v[50:51], v0, off offset:512
	v_cvt_pk_bf16_f32 v0, v32, s0
	global_store_short v[50:51], v0, off offset:1024
	v_cvt_pk_bf16_f32 v0, v33, s0
	global_store_short v[50:51], v0, off offset:1536
	v_lshl_add_u64 v[50:51], v[50:51], 0, s[52:53]
	v_cvt_pk_bf16_f32 v0, v26, s0
	global_store_short v[50:51], v0, off
	v_cvt_pk_bf16_f32 v0, v27, s0
	global_store_short v[50:51], v0, off offset:512
	v_cvt_pk_bf16_f32 v0, v28, s0
	global_store_short v[50:51], v0, off offset:1024
	v_cvt_pk_bf16_f32 v0, v29, s0
	global_store_short v[50:51], v0, off offset:1536
	v_lshl_add_u64 v[50:51], v[50:51], 0, s[52:53]
	v_cvt_pk_bf16_f32 v0, v14, s0
	global_store_short v[50:51], v0, off
	v_cvt_pk_bf16_f32 v0, v15, s0
	global_store_short v[50:51], v0, off offset:512
	v_cvt_pk_bf16_f32 v0, v16, s0
	global_store_short v[50:51], v0, off offset:1024
	v_cvt_pk_bf16_f32 v0, v17, s0
	global_store_short v[50:51], v0, off offset:1536
	v_lshl_add_u64 v[50:51], v[50:51], 0, s[52:53]
	v_cvt_pk_bf16_f32 v0, v10, s0
	global_store_short v[50:51], v0, off
	v_cvt_pk_bf16_f32 v0, v11, s0
	global_store_short v[50:51], v0, off offset:512
	v_cvt_pk_bf16_f32 v0, v12, s0
	global_store_short v[50:51], v0, off offset:1024
	v_cvt_pk_bf16_f32 v0, v13, s0
	global_store_short v[50:51], v0, off offset:1536
	v_lshl_add_u64 v[50:51], v[50:51], 0, s[52:53]
	v_cvt_pk_bf16_f32 v0, v6, s0
	global_store_short v[50:51], v0, off
	v_cvt_pk_bf16_f32 v0, v7, s0
	global_store_short v[50:51], v0, off offset:512
	v_cvt_pk_bf16_f32 v0, v8, s0
	global_store_short v[50:51], v0, off offset:1024
	v_cvt_pk_bf16_f32 v0, v9, s0
	global_store_short v[50:51], v0, off offset:1536
	v_lshl_add_u64 v[50:51], v[50:51], 0, s[52:53]
	v_cvt_pk_bf16_f32 v0, v2, s0
	global_store_short v[50:51], v0, off
	v_cvt_pk_bf16_f32 v0, v3, s0
	global_store_short v[50:51], v0, off offset:512
	v_cvt_pk_bf16_f32 v0, v4, s0
	global_store_short v[50:51], v0, off offset:1024
	v_cvt_pk_bf16_f32 v0, v5, s0
	s_add_u32 s60, s66, vcc_lo
	global_store_short v[50:51], v0, off offset:1536
	v_lshl_add_u64 v[50:51], v[50:51], 0, s[52:53]
	s_addc_u32 s61, s67, s96
	s_and_saveexec_b64 s[52:53], s[56:57]
	s_cbranch_execz .LBB0_290
	v_lshl_add_u64 v[50:51], v[106:107], 2, s[60:61]
	global_store_dword v[50:51], v152, off
